# mLSTM pass-C and pass-A MFMA sections: LDS fragment reads hoisted ahead of their MFMAs into free registers (counted lgkmcnt waits)
# speedup vs baseline: 1.0063x; 1.0063x over previous
.LBB0_546:
	s_waitcnt lgkmcnt(0)
	s_barrier
	ds_read_b128 v[62:65], v172
	ds_read_b128 v[66:69], v172 offset:64
	ds_read_b128 v[70:73], v172 offset:128
	ds_read_b128 v[74:77], v172 offset:192
	ds_read2st64_b32 v[78:79], v150 offset1:2
	ds_read_b128 v[88:91], v152 offset:17408
	ds_read_b128 v[132:135], v152 offset:17472
	ds_read_b128 v[182:185], v152 offset:26176
	ds_read_b128 v[192:195], v152 offset:17536
	ds_read_b128 v[196:199], v152 offset:17600
	ds_read_b128 v[200:203], v151
	ds_read_b128 v[204:207], v152 offset:21824
	ds_read_b128 v[208:211], v152 offset:21760
	ds_read_b128 v[218:221], v152 offset:21888
	s_waitcnt lgkmcnt(13)
	ds_read_b128 v[240:243], v152 offset:21952
	s_nop 0
	s_nop 0
	s_nop 0
	s_nop 0
	s_nop 0
	v_readlane_b32 s12, v255, 1
	v_readlane_b32 s13, v255, 2
	s_mov_b32 s9, 0x5040100
	s_nop 0
	s_waitcnt lgkmcnt(10)
	v_sub_f32_e32 v36, v78, v79
	ds_read2st64_b32 v[34:35], v150 offset0:3 offset1:5
	s_nop 0
	s_nop 0
	s_nop 0
	s_waitcnt lgkmcnt(10)
	v_mfma_f32_16x16x32_bf16 v[24:27], v[88:91], v[62:65], 0
	ds_read_b128 v[88:91], v151 offset:64
	s_nop 0
	s_nop 0
	s_waitcnt lgkmcnt(10)
	v_mfma_f32_16x16x32_bf16 v[24:27], v[132:135], v[66:69], v[24:27]
	ds_read_b128 v[132:135], v152 offset:26112
	s_nop 0
	s_nop 0
	s_waitcnt lgkmcnt(9)
	v_mfma_f32_16x16x32_bf16 v[24:27], v[192:195], v[70:73], v[24:27]
	ds_read_b128 v[192:195], v152 offset:26240
	s_nop 0
	s_nop 0
	s_waitcnt lgkmcnt(9)
	v_mfma_f32_16x16x32_bf16 v[24:27], v[196:199], v[74:77], v[24:27]
	ds_read_b128 v[196:199], v152 offset:26304
	s_nop 0
	s_nop 0
	s_waitcnt lgkmcnt(9)
	v_add_f32_e32 v28, v36, v200
	v_mul_f32_e32 v28, 0x3fb8aa3b, v28
	v_exp_f32_e32 v28, v28
	s_nop 2
	v_mul_f32_e32 v24, v24, v28
	v_cndmask_b32_e64 v28, v24, 0, s[12:13]
	v_add_f32_e32 v24, v36, v201
	v_mul_f32_e32 v24, 0x3fb8aa3b, v24
	v_exp_f32_e32 v24, v24
	v_readlane_b32 s12, v255, 3
	v_readlane_b32 s13, v255, 4
	v_mul_f32_e32 v24, v25, v24
	s_nop 0
	v_cndmask_b32_e64 v29, 0, v24, s[12:13]
	v_add_f32_e32 v24, v36, v202
	v_add_f32_e32 v25, v36, v203
	ds_read_b128 v[200:203], v151 offset:128
	v_mul_f32_e32 v24, 0x3fb8aa3b, v24
	v_mul_f32_e32 v25, 0x3fb8aa3b, v25
	v_exp_f32_e32 v24, v24
	v_exp_f32_e32 v25, v25
	v_readlane_b32 s12, v255, 7
	v_readlane_b32 s13, v255, 8
	s_nop 0
	v_pk_mul_f32 v[26:27], v[26:27], v[24:25]
	v_cvt_pk_bf16_f32 v24, v28, v29
	v_cvt_pk_bf16_f32 v25, v26, v27
	v_cndmask_b32_e64 v26, v25, 0, s[12:13]
	v_readlane_b32 s12, v255, 5
	v_lshrrev_b32_e32 v25, 16, v25
	v_readlane_b32 s13, v255, 6
	s_nop 1
	v_cndmask_b32_e64 v25, v25, 0, s[12:13]
	v_perm_b32 v25, v25, v26, s9
	s_nop 0
	s_nop 0
	s_waitcnt lgkmcnt(8)
	v_mfma_f32_16x16x32_bf16 v[26:29], v[208:211], v[62:65], 0
	ds_read_b128 v[208:211], v152 offset:30528
	v_readlane_b32 s12, v255, 11
	v_readlane_b32 s13, v255, 12
	v_mfma_f32_16x16x32_bf16 v[26:29], v[204:207], v[66:69], v[26:29]
	ds_read_b128 v[204:207], v152 offset:30464
	s_nop 0
	s_nop 0
	s_waitcnt lgkmcnt(9)
	v_mfma_f32_16x16x32_bf16 v[26:29], v[218:221], v[70:73], v[26:29]
	ds_read_b128 v[218:221], v152 offset:30592
	s_nop 0
	s_nop 0
	s_waitcnt lgkmcnt(9)
	v_mfma_f32_16x16x32_bf16 v[26:29], v[240:243], v[74:77], v[26:29]
	ds_read_b128 v[240:243], v152 offset:30656
	s_nop 0
	s_nop 0
	s_waitcnt lgkmcnt(8)
	v_add_f32_e32 v30, v36, v88
	v_add_f32_e32 v31, v36, v89
	v_mul_f32_e32 v30, 0x3fb8aa3b, v30
	v_mul_f32_e32 v31, 0x3fb8aa3b, v31
	v_exp_f32_e32 v30, v30
	v_exp_f32_e32 v31, v31
	s_nop 0
	v_pk_mul_f32 v[26:27], v[26:27], v[30:31]
	v_add_f32_e32 v30, v36, v90
	v_add_f32_e32 v31, v36, v91
	ds_read_b128 v[88:91], v151 offset:192
	v_mul_f32_e32 v30, 0x3fb8aa3b, v30
	v_mul_f32_e32 v31, 0x3fb8aa3b, v31
	v_exp_f32_e32 v30, v30
	v_exp_f32_e32 v31, v31
	v_cvt_pk_bf16_f32 v26, v26, v27
	v_cndmask_b32_e64 v27, v26, 0, s[12:13]
	v_readlane_b32 s12, v255, 9
	v_lshrrev_b32_e32 v26, 16, v26
	v_readlane_b32 s13, v255, 10
	v_pk_mul_f32 v[28:29], v[28:29], v[30:31]
	s_nop 0
	v_cndmask_b32_e64 v26, v26, 0, s[12:13]
	v_readlane_b32 s12, v255, 15
	v_perm_b32 v26, v26, v27, s9
	v_cvt_pk_bf16_f32 v27, v28, v29
	v_readlane_b32 s13, v255, 16
	s_nop 1
	v_cndmask_b32_e64 v28, v27, 0, s[12:13]
	v_readlane_b32 s12, v255, 13
	v_lshrrev_b32_e32 v27, 16, v27
	v_readlane_b32 s13, v255, 14
	s_nop 1
	v_cndmask_b32_e64 v27, v27, 0, s[12:13]
	v_perm_b32 v27, v27, v28, s9
	s_nop 0
	s_nop 0
	s_waitcnt lgkmcnt(8)
	v_mfma_f32_16x16x32_bf16 v[28:31], v[132:135], v[62:65], 0
	ds_read_b64_tr_b16 v[132:133], v156 offset:34816
	v_readlane_b32 s12, v255, 21
	v_readlane_b32 s13, v255, 22
	v_mfma_f32_16x16x32_bf16 v[28:31], v[182:185], v[66:69], v[28:31]
	ds_read_b64_tr_b16 v[182:183], v156 offset:34848
	ds_read_b64_tr_b16 v[134:135], v156 offset:39680
	s_nop 0
	s_nop 0
	s_waitcnt lgkmcnt(10)
	v_mfma_f32_16x16x32_bf16 v[28:31], v[192:195], v[70:73], v[28:31]
	ds_read_b64_tr_b16 v[192:193], v156 offset:44544
	ds_read_b64_tr_b16 v[194:195], v156 offset:49408
	s_nop 0
	s_nop 0
	s_waitcnt lgkmcnt(11)
	v_mfma_f32_16x16x32_bf16 v[28:31], v[196:199], v[74:77], v[28:31]
	ds_read_b128 v[196:199], v173 offset:54272
	s_nop 0
	s_nop 0
	s_waitcnt lgkmcnt(11)
	v_add_f32_e32 v32, v36, v200
	v_add_f32_e32 v33, v36, v201
	v_mul_f32_e32 v32, 0x3fb8aa3b, v32
	v_mul_f32_e32 v33, 0x3fb8aa3b, v33
	v_exp_f32_e32 v32, v32
	v_exp_f32_e32 v33, v33
	s_nop 0
	v_pk_mul_f32 v[28:29], v[28:29], v[32:33]
	v_add_f32_e32 v32, v36, v202
	v_add_f32_e32 v33, v36, v203
	ds_read_b128 v[200:203], v173 offset:54336
	v_mul_f32_e32 v32, 0x3fb8aa3b, v32
	v_mul_f32_e32 v33, 0x3fb8aa3b, v33
	v_exp_f32_e32 v32, v32
	v_exp_f32_e32 v33, v33
	v_cvt_pk_bf16_f32 v28, v28, v29
	v_cndmask_b32_e64 v29, v28, 0, s[12:13]
	v_readlane_b32 s12, v255, 19
	v_lshrrev_b32_e32 v28, 16, v28
	v_readlane_b32 s13, v255, 20
	v_pk_mul_f32 v[30:31], v[30:31], v[32:33]
	s_nop 0
	v_cndmask_b32_e64 v28, v28, 0, s[12:13]
	v_readlane_b32 s12, v255, 25
	v_perm_b32 v28, v28, v29, s9
	v_cvt_pk_bf16_f32 v29, v30, v31
	v_readlane_b32 s13, v255, 26
	s_nop 1
	v_cndmask_b32_e64 v30, v29, 0, s[12:13]
	v_readlane_b32 s12, v255, 23
	v_lshrrev_b32_e32 v29, 16, v29
	v_readlane_b32 s13, v255, 24
	s_nop 1
	v_cndmask_b32_e64 v29, v29, 0, s[12:13]
	v_perm_b32 v29, v29, v30, s9
	s_nop 0
	s_nop 0
	s_waitcnt lgkmcnt(10)
	v_mfma_f32_16x16x32_bf16 v[30:33], v[204:207], v[62:65], 0
	ds_read_b128 v[204:207], v173 offset:54400
	v_readlane_b32 s12, v255, 29
	v_readlane_b32 s13, v255, 30
	v_mfma_f32_16x16x32_bf16 v[30:33], v[208:211], v[66:69], v[30:33]
	ds_read_b128 v[208:211], v173 offset:54464
	ds_read_b64_tr_b16 v[184:185], v156 offset:39712
	s_nop 0
	s_nop 0
	s_waitcnt lgkmcnt(12)
	v_mfma_f32_16x16x32_bf16 v[30:33], v[218:221], v[70:73], v[30:33]
	ds_read_b64_tr_b16 v[218:219], v156 offset:44576
	ds_read_b64_tr_b16 v[220:221], v156 offset:49440
	s_nop 0
	s_nop 0
	s_waitcnt lgkmcnt(13)
	v_mfma_f32_16x16x32_bf16 v[30:33], v[240:243], v[74:77], v[30:33]
	ds_read_b128 v[240:243], v174 offset:54272
	s_nop 0
	s_nop 0
	s_waitcnt lgkmcnt(13)
	v_add_f32_e32 v37, v36, v88
	v_mul_f32_e32 v37, 0x3fb8aa3b, v37
	v_exp_f32_e32 v38, v37
	v_add_f32_e32 v37, v36, v89
	v_mul_f32_e32 v37, 0x3fb8aa3b, v37
	v_exp_f32_e32 v39, v37
	v_add_f32_e32 v37, v36, v90
	v_add_f32_e32 v36, v36, v91
	ds_read_b128 v[88:91], v174 offset:54336
	v_mul_f32_e32 v37, 0x3fb8aa3b, v37
	v_mul_f32_e32 v36, 0x3fb8aa3b, v36
	v_pk_mul_f32 v[30:31], v[30:31], v[38:39]
	v_exp_f32_e32 v38, v37
	v_exp_f32_e32 v39, v36
	v_cvt_pk_bf16_f32 v30, v30, v31
	v_cndmask_b32_e64 v31, v30, 0, s[12:13]
	v_readlane_b32 s12, v255, 27
	v_pk_mul_f32 v[32:33], v[32:33], v[38:39]
	s_nop 0
	s_nop 0
	s_nop 0
	s_nop 0
	s_nop 0
	s_nop 0
	s_nop 0
	s_nop 0
	s_waitcnt lgkmcnt(8)
	v_mfma_f32_16x16x32_bf16 v[46:49], v[196:199], v[62:65], 0
	ds_read_b128 v[196:199], v174 offset:54400
	v_lshrrev_b32_e32 v30, 16, v30
	v_readlane_b32 s13, v255, 28
	s_nop 0
	s_waitcnt lgkmcnt(8)
	v_mfma_f32_16x16x32_bf16 v[46:49], v[200:203], v[66:69], v[46:49]
	ds_read_b128 v[200:203], v174 offset:54464
	s_nop 0
	v_cndmask_b32_e64 v30, v30, 0, s[12:13]
	v_readlane_b32 s12, v255, 33
	s_nop 0
	s_waitcnt lgkmcnt(8)
	v_mfma_f32_16x16x32_bf16 v[46:49], v[204:207], v[70:73], v[46:49]
	ds_read_b64_tr_b16 v[204:205], v156 offset:34880
	ds_read_b64_tr_b16 v[206:207], v156 offset:39744
	s_nop 0
	v_perm_b32 v30, v30, v31, s9
	v_cvt_pk_bf16_f32 v31, v32, v33
	v_readlane_b32 s13, v255, 34
	v_mfma_f32_16x16x32_bf16 v[36:39], v[132:135], v[24:27], 0
	ds_read_b64_tr_b16 v[132:133], v156 offset:44608
	ds_read_b64_tr_b16 v[134:135], v156 offset:49472
	s_nop 0
	v_cndmask_b32_e64 v32, v31, 0, s[12:13]
	v_readlane_b32 s12, v255, 31
	v_lshrrev_b32_e32 v31, 16, v31
	v_readlane_b32 s13, v255, 32
	s_nop 0
	s_waitcnt lgkmcnt(11)
	v_mfma_f32_16x16x32_bf16 v[46:49], v[208:211], v[74:77], v[46:49]
	ds_read_b128 v[208:211], v175 offset:54272
	v_cndmask_b32_e64 v31, v31, 0, s[12:13]
	v_perm_b32 v31, v31, v32, s9
	s_nop 1
	v_mfma_f32_16x16x32_bf16 v[36:39], v[192:195], v[28:31], v[36:39]
	ds_read_b128 v[192:195], v175 offset:54336
	s_nop 7
	v_pk_fma_f32 v[32:33], v[34:35], v[48:49], v[38:39] op_sel_hi:[0,1,1]
	v_pk_fma_f32 v[36:37], v[34:35], v[46:47], v[36:37] op_sel_hi:[0,1,1]
	s_nop 0
	s_nop 0
	s_nop 0
	s_nop 0
	s_nop 0
	s_nop 0
	s_waitcnt lgkmcnt(9)
	v_mfma_f32_16x16x32_bf16 v[48:51], v[240:243], v[62:65], 0
	ds_read_b128 v[240:243], v175 offset:54400
	s_nop 0
	s_waitcnt lgkmcnt(9)
	v_mfma_f32_16x16x32_bf16 v[48:51], v[88:91], v[66:69], v[48:51]
	ds_read_b128 v[88:91], v175 offset:54464
	s_nop 0
	s_nop 0
	s_waitcnt lgkmcnt(9)
	v_mfma_f32_16x16x32_bf16 v[48:51], v[196:199], v[70:73], v[48:51]
	ds_read_b64_tr_b16 v[196:197], v154 offset:34816
	ds_read_b64_tr_b16 v[198:199], v154 offset:39680
	s_nop 0
	v_mfma_f32_16x16x32_bf16 v[38:41], v[182:185], v[24:27], 0
	ds_read_b64_tr_b16 v[182:183], v154 offset:44544
	ds_read_b64_tr_b16 v[184:185], v154 offset:49408
	s_nop 0
	s_waitcnt lgkmcnt(12)
	v_mfma_f32_16x16x32_bf16 v[48:51], v[200:203], v[74:77], v[48:51]
	ds_read_b128 v[200:203], v176 offset:54272
	v_mfma_f32_16x16x32_bf16 v[40:43], v[218:221], v[28:31], v[38:41]
	ds_read_b128 v[218:221], v176 offset:54336
	s_nop 7
	v_pk_fma_f32 v[38:39], v[34:35], v[50:51], v[42:43] op_sel_hi:[0,1,1]
	v_pk_fma_f32 v[40:41], v[34:35], v[48:49], v[40:41] op_sel_hi:[0,1,1]
	s_nop 0
	s_nop 0
	s_nop 0
	s_nop 0
	s_nop 0
	s_nop 0
	s_nop 0
	s_waitcnt lgkmcnt(9)
	v_mfma_f32_16x16x32_bf16 v[50:53], v[208:211], v[62:65], 0
	ds_read_b128 v[208:211], v176 offset:54400
	s_nop 0
	s_waitcnt lgkmcnt(9)
	v_mfma_f32_16x16x32_bf16 v[50:53], v[192:195], v[66:69], v[50:53]
	ds_read_b128 v[192:195], v176 offset:54464
	s_nop 0
	s_nop 0
	s_waitcnt lgkmcnt(9)
	v_mfma_f32_16x16x32_bf16 v[50:53], v[240:243], v[70:73], v[50:53]
	ds_read_b64_tr_b16 v[240:241], v153 offset:35072
	ds_read_b64_tr_b16 v[242:243], v153 offset:39936
	s_nop 0
	v_mfma_f32_16x16x32_bf16 v[42:45], v[204:207], v[24:27], 0
	ds_read_b64_tr_b16 v[204:205], v153 offset:44800
	ds_read_b64_tr_b16 v[206:207], v153 offset:49664
	s_nop 0
	s_waitcnt lgkmcnt(12)
	v_mfma_f32_16x16x32_bf16 v[50:53], v[88:91], v[74:77], v[50:53]
	ds_read_b128 v[88:91], v157 offset:34816
	v_mfma_f32_16x16x32_bf16 v[44:47], v[132:135], v[28:31], v[42:45]
	ds_read_b128 v[132:135], v157 offset:34880
	s_nop 7
	v_pk_fma_f32 v[42:43], v[34:35], v[52:53], v[46:47] op_sel_hi:[0,1,1]
	v_pk_fma_f32 v[44:45], v[34:35], v[50:51], v[44:45] op_sel_hi:[0,1,1]
	s_nop 0
	s_nop 0
	s_nop 0
	s_nop 0
	s_nop 0
	s_nop 0
	s_nop 0
	s_waitcnt lgkmcnt(9)
	v_mfma_f32_16x16x32_bf16 v[54:57], v[200:203], v[62:65], 0
	ds_read_b128 v[200:203], v157 offset:34944
	s_nop 0
	s_waitcnt lgkmcnt(9)
	v_mfma_f32_16x16x32_bf16 v[54:57], v[218:221], v[66:69], v[54:57]
	ds_read_b128 v[218:221], v157 offset:35008
	s_nop 0
	s_nop 0
	s_waitcnt lgkmcnt(9)
	v_mfma_f32_16x16x32_bf16 v[54:57], v[208:211], v[70:73], v[54:57]
	s_nop 0
	v_mfma_f32_16x16x32_bf16 v[46:49], v[196:199], v[24:27], 0
	s_nop 0
	s_waitcnt lgkmcnt(8)
	v_mfma_f32_16x16x32_bf16 v[54:57], v[192:195], v[74:77], v[54:57]
	v_mfma_f32_16x16x32_bf16 v[46:49], v[182:185], v[28:31], v[46:49]
	s_nop 7
	v_pk_fma_f32 v[58:59], v[34:35], v[56:57], v[48:49] op_sel_hi:[0,1,1]
	v_pk_fma_f32 v[60:61], v[34:35], v[54:55], v[46:47] op_sel_hi:[0,1,1]
	s_nop 0
	s_nop 0
	s_nop 0
	s_nop 0
	s_nop 0
	s_nop 0
	s_waitcnt lgkmcnt(3)
	v_mfma_f32_16x16x32_bf16 v[20:23], v[88:91], v[62:65], 0
	s_nop 0
	s_nop 0
	s_waitcnt lgkmcnt(2)
	v_mfma_f32_16x16x32_bf16 v[16:19], v[132:135], v[66:69], v[20:23]
	s_nop 4
	s_nop 0
	s_nop 0
	s_waitcnt lgkmcnt(1)
	v_mfma_f32_16x16x32_bf16 v[12:15], v[200:203], v[70:73], v[16:19]
	s_nop 2
	s_nop 0
	s_nop 0
	s_waitcnt lgkmcnt(0)
	v_mfma_f32_16x16x32_bf16 v[8:11], v[218:221], v[74:77], v[12:15]
	v_mfma_f32_16x16x32_bf16 v[10:13], v[240:243], v[24:27], 0
	v_mfma_f32_16x16x32_bf16 v[10:13], v[204:207], v[28:31], v[10:13]
	s_nop 7
	v_fmac_f32_e32 v10, v34, v8
	v_max_f32_e32 v8, v35, v35
	v_max_f32_e64 v8, |v10|, v8
	v_div_scale_f32 v9, s[12:13], v8, v8, 1.0
	v_rcp_f32_e32 v10, v9
	s_nop 0
	v_fma_f32 v11, -v9, v10, 1.0
	v_fmac_f32_e32 v10, v11, v10
	v_div_scale_f32 v11, vcc, 1.0, v8, 1.0
	v_mul_f32_e32 v12, v11, v10
	v_fma_f32 v13, -v9, v12, v11
	v_fmac_f32_e32 v12, v13, v10
	v_fma_f32 v9, -v9, v12, v11
	v_div_fmas_f32 v9, v9, v10, v12
	v_div_fixup_f32 v10, v9, v8, 1.0
	v_pk_mul_f32 v[20:21], v[32:33], v[10:11] op_sel_hi:[1,0]
	v_pk_mul_f32 v[22:23], v[36:37], v[10:11] op_sel_hi:[1,0]
	v_mul_f32_e32 v9, v21, v21
	v_mul_f32_e32 v8, v23, v23
	v_fmac_f32_e32 v8, v22, v22
	v_fmac_f32_e32 v9, v20, v20
	v_pk_mul_f32 v[16:17], v[38:39], v[10:11] op_sel_hi:[1,0]
	v_pk_mul_f32 v[18:19], v[40:41], v[10:11] op_sel_hi:[1,0]
	v_add_f32_e32 v8, v8, v9
	v_mul_f32_e32 v9, v19, v19
	v_mul_f32_e32 v11, v17, v17
	v_fmac_f32_e32 v9, v18, v18
	v_fmac_f32_e32 v11, v16, v16
	v_add_f32_e32 v9, v9, v11
	v_pk_mul_f32 v[12:13], v[42:43], v[10:11] op_sel_hi:[1,0]
	v_pk_mul_f32 v[14:15], v[44:45], v[10:11] op_sel_hi:[1,0]
	v_add_f32_e32 v8, v8, v9
	v_mul_f32_e32 v9, v15, v15
	v_mul_f32_e32 v11, v13, v13
	v_fmac_f32_e32 v9, v14, v14
	v_fmac_f32_e32 v11, v12, v12
	v_add_f32_e32 v9, v9, v11
	v_add_f32_e32 v24, v9, v8
	v_pk_mul_f32 v[8:9], v[58:59], v[10:11] op_sel_hi:[1,0]
	v_pk_mul_f32 v[10:11], v[60:61], v[10:11] op_sel_hi:[1,0]
	v_mul_f32_e32 v26, v9, v9
	v_mul_f32_e32 v25, v11, v11
	v_fmac_f32_e32 v25, v10, v10
	v_fmac_f32_e32 v26, v8, v8
	v_add_f32_e32 v25, v25, v26
	v_and_b32_e32 v26, 64, v216
	v_add_f32_e32 v24, v25, v24
	v_xor_b32_e32 v25, 16, v216
	v_add_u32_e32 v26, 64, v26
	v_cmp_lt_i32_e32 vcc, v25, v26
	s_nop 1
	v_cndmask_b32_e32 v25, v216, v25, vcc
	v_lshlrev_b32_e32 v25, 2, v25
	ds_bpermute_b32 v25, v25, v24
	s_nop 0
	s_waitcnt lgkmcnt(0)
	v_add_f32_e32 v24, v24, v25
	v_xor_b32_e32 v25, 32, v216
	v_cmp_lt_i32_e32 vcc, v25, v26
	s_nop 1
	v_cndmask_b32_e32 v25, v216, v25, vcc
	v_lshlrev_b32_e32 v25, 2, v25
	ds_bpermute_b32 v25, v25, v24
	s_waitcnt lgkmcnt(0)
	s_and_saveexec_b64 s[12:13], s[68:69]
	s_cbranch_execz .LBB0_548
	s_waitcnt lgkmcnt(0)
	v_add_f32_e32 v24, v24, v25
	ds_write_b32 v155, v24

.LBB0_570:
	s_waitcnt lgkmcnt(0)
	s_barrier
	ds_read_b64_tr_b16 v[28:29], v179 offset:17408
	ds_read_b64_tr_b16 v[30:31], v179 offset:18496
	ds_read_b128 v[32:35], v164
	ds_read_b128 v[36:39], v164 offset:16
	ds_read_b64_tr_b16 v[40:41], v179 offset:26112
	ds_read_b64_tr_b16 v[42:43], v179 offset:27200
	ds_read_b128 v[44:47], v164 offset:128
	ds_read_b128 v[48:51], v164 offset:144
	ds_read_b64_tr_b16 v[52:53], v190 offset:34816
	ds_read_b64_tr_b16 v[54:55], v190 offset:36032
	ds_read_b64_tr_b16 v[56:57], v190 offset:44544
	ds_read_b64_tr_b16 v[58:59], v190 offset:45760
	ds_read_b64_tr_b16 v[60:61], v190 offset:34848
	ds_read_b64_tr_b16 v[62:63], v190 offset:36064
	s_waitcnt lgkmcnt(13)
	ds_read_b64_tr_b16 v[64:65], v190 offset:44576
	s_waitcnt lgkmcnt(13)
	ds_read_b64_tr_b16 v[66:67], v190 offset:45792
	s_waitcnt lgkmcnt(13)
	ds_read_b64_tr_b16 v[68:69], v190 offset:34880
	s_waitcnt lgkmcnt(13)
	ds_read_b64_tr_b16 v[70:71], v190 offset:36096
	s_waitcnt lgkmcnt(13)
	ds_read_b64_tr_b16 v[72:73], v190 offset:44608
	s_waitcnt lgkmcnt(13)
	ds_read_b64_tr_b16 v[74:75], v190 offset:45824
	s_waitcnt lgkmcnt(13)
	ds_read_b64_tr_b16 v[76:77], v190 offset:34912
	s_waitcnt lgkmcnt(13)
	ds_read_b64_tr_b16 v[78:79], v190 offset:36128
	s_waitcnt lgkmcnt(13)
	ds_read_b64_tr_b16 v[88:89], v190 offset:44640
	s_waitcnt lgkmcnt(13)
	ds_read_b64_tr_b16 v[90:91], v190 offset:45856
	s_waitcnt lgkmcnt(13)
	ds_read_b64_tr_b16 v[132:133], v190 offset:34944
	s_waitcnt lgkmcnt(13)
	ds_read_b64_tr_b16 v[134:135], v190 offset:36160
	s_waitcnt lgkmcnt(13)
	ds_read_b64_tr_b16 v[192:193], v190 offset:44672
	s_waitcnt lgkmcnt(13)
	ds_read_b64_tr_b16 v[194:195], v190 offset:45888
	s_waitcnt lgkmcnt(13)
	ds_read_b64_tr_b16 v[196:197], v190 offset:34976
	s_waitcnt lgkmcnt(13)
	ds_read_b64_tr_b16 v[198:199], v190 offset:36192
	s_waitcnt lgkmcnt(13)
	ds_read_b64_tr_b16 v[200:201], v190 offset:44704
	s_waitcnt lgkmcnt(13)
	ds_read_b64_tr_b16 v[202:203], v190 offset:45920
	s_waitcnt lgkmcnt(13)
	ds_read_b64_tr_b16 v[204:205], v190 offset:35008
	s_waitcnt lgkmcnt(13)
	ds_read_b64_tr_b16 v[206:207], v190 offset:36224
	s_waitcnt lgkmcnt(13)
	ds_read_b64_tr_b16 v[208:209], v190 offset:44736
	s_waitcnt lgkmcnt(13)
	ds_read_b64_tr_b16 v[210:211], v190 offset:45952
	s_waitcnt lgkmcnt(13)
	ds_read_b64_tr_b16 v[224:225], v190 offset:35040
	s_waitcnt lgkmcnt(13)
	ds_read_b64_tr_b16 v[226:227], v190 offset:36256
	s_waitcnt lgkmcnt(13)
	ds_read_b64_tr_b16 v[228:229], v190 offset:44768
	s_waitcnt lgkmcnt(13)
	ds_read_b64_tr_b16 v[230:231], v190 offset:45984
	s_waitcnt lgkmcnt(13)
	ds_read_b64_tr_b16 v[232:233], v190 offset:35072
	s_waitcnt lgkmcnt(13)
	ds_read_b64_tr_b16 v[234:235], v190 offset:36288
	s_nop 0
	s_nop 0
	s_nop 0
	s_nop 0
	v_readlane_b32 s72, v251, 4
	s_nop 0
	v_lshlrev_b32_e32 v20, 16, v28
	v_and_b32_e32 v21, 0xffff0000, v28
	s_nop 0
	v_pk_mul_f32 v[8:9], v[32:33], v[20:21]
	s_lshl_b64 s[8:9], s[26:27], 23
	v_cvt_pk_bf16_f32 v12, v8, v9
	v_lshlrev_b32_e32 v8, 16, v29
	v_and_b32_e32 v9, 0xffff0000, v29
	v_pk_mul_f32 v[8:9], v[34:35], v[8:9]
	v_readlane_b32 s86, v251, 18
	v_cvt_pk_bf16_f32 v13, v8, v9
	v_lshlrev_b32_e32 v8, 16, v30
	v_and_b32_e32 v9, 0xffff0000, v30
	s_nop 0
	v_pk_mul_f32 v[8:9], v[36:37], v[8:9]
	v_readlane_b32 s87, v251, 19
	v_cvt_pk_bf16_f32 v14, v8, v9
	v_lshlrev_b32_e32 v8, 16, v31
	v_and_b32_e32 v9, 0xffff0000, v31
	v_pk_mul_f32 v[8:9], v[38:39], v[8:9]
	s_add_u32 s8, s86, s8
	v_cvt_pk_bf16_f32 v15, v8, v9
	s_nop 0
	s_nop 0
	s_nop 0
	s_nop 0
	s_addc_u32 s9, s87, s9
	s_nop 0
	v_lshlrev_b32_e32 v24, 16, v40
	v_and_b32_e32 v25, 0xffff0000, v40
	v_lshlrev_b32_e32 v20, 16, v41
	v_and_b32_e32 v21, 0xffff0000, v41
	s_nop 0
	v_pk_mul_f32 v[8:9], v[44:45], v[24:25]
	v_pk_mul_f32 v[10:11], v[46:47], v[20:21]
	v_cvt_pk_bf16_f32 v8, v8, v9
	v_cvt_pk_bf16_f32 v9, v10, v11
	v_lshlrev_b32_e32 v10, 16, v42
	v_and_b32_e32 v11, 0xffff0000, v42
	s_nop 0
	v_pk_mul_f32 v[10:11], v[48:49], v[10:11]
	v_lshlrev_b32_e32 v16, 16, v43
	v_and_b32_e32 v17, 0xffff0000, v43
	v_pk_mul_f32 v[16:17], v[50:51], v[16:17]
	v_cvt_pk_bf16_f32 v10, v10, v11
	v_cvt_pk_bf16_f32 v11, v16, v17
	s_nop 0
	s_nop 0
	s_nop 0
	s_nop 0
	s_nop 0
	v_mfma_f32_16x16x32_bf16 v[16:19], v[12:15], v[52:55], 0
	s_and_b32 s12, s65, 0x7f
	s_mul_i32 s12, s12, 0x9000
	s_add_u32 s12, s8, s12
	s_addc_u32 s13, s9, 0
	s_lshl_b64 s[8:9], s[10:11], 1
	s_nop 0
	v_mfma_f32_16x16x32_bf16 v[16:19], v[8:11], v[56:59], v[16:19]
	s_add_u32 s8, s12, s8
	s_addc_u32 s9, s13, s9
	v_lshlrev_b32_e32 v180, 1, v102
	v_lshl_add_u64 v[24:25], s[8:9], 0, v[180:181]
	v_mov_b32_e32 v131, v181
	s_nop 2
	v_cvt_pk_bf16_f32 v20, v16, v17
	v_cvt_pk_bf16_f32 v21, v18, v19
	v_lshl_add_u64 v[16:17], v[24:25], 0, v[130:131]
	global_store_dwordx2 v[16:17], v[20:21], off
	s_nop 0
	s_nop 0
	s_nop 0
	s_nop 0
	s_nop 0
	v_mfma_f32_16x16x32_bf16 v[18:21], v[12:15], v[60:63], 0
	s_movk_i32 s8, 0x2000
	v_add_co_u32_e32 v26, vcc, s8, v16
	s_nop 0
	v_mfma_f32_16x16x32_bf16 v[18:21], v[8:11], v[64:67], v[18:21]
	v_addc_co_u32_e32 v27, vcc, 0, v17, vcc
	s_movk_i32 s8, 0x4000
	v_readlane_b32 s84, v251, 16
	v_readlane_b32 s85, v251, 17
	s_nop 3
	v_cvt_pk_bf16_f32 v18, v18, v19
	v_cvt_pk_bf16_f32 v19, v20, v21
	global_store_dwordx2 v[26:27], v[18:19], off offset:-4096
	s_nop 0
	s_nop 0
	s_nop 0
	s_nop 0
	s_nop 0
	v_mfma_f32_16x16x32_bf16 v[18:21], v[12:15], v[68:71], 0
	v_readlane_b32 s84, v254, 37
	v_readlane_b32 s86, v254, 39
	v_readlane_b32 s85, v254, 38
	s_nop 0
	v_mfma_f32_16x16x32_bf16 v[18:21], v[8:11], v[72:75], v[18:21]
	v_readlane_b32 s87, v254, 40
	v_readlane_b32 s73, v251, 5
	v_readlane_b32 s74, v251, 6
	v_readlane_b32 s75, v251, 7
	v_readlane_b32 s76, v251, 8
	s_nop 2
	v_cvt_pk_bf16_f32 v18, v18, v19
	v_cvt_pk_bf16_f32 v19, v20, v21
	global_store_dwordx2 v[26:27], v[18:19], off
	s_nop 0
	s_nop 0
	s_nop 0
	s_nop 0
	s_nop 0
	v_mfma_f32_16x16x32_bf16 v[18:21], v[12:15], v[76:79], 0
	v_add_co_u32_e32 v26, vcc, s8, v16
	s_movk_i32 s8, 0x6000
	s_nop 0
	v_mfma_f32_16x16x32_bf16 v[18:21], v[8:11], v[88:91], v[18:21]
	v_addc_co_u32_e32 v27, vcc, 0, v17, vcc
	v_readlane_b32 s77, v251, 9
	v_readlane_b32 s78, v251, 10
	v_readlane_b32 s79, v251, 11
	s_nop 3
	v_cvt_pk_bf16_f32 v18, v18, v19
	v_cvt_pk_bf16_f32 v19, v20, v21
	global_store_dwordx2 v[26:27], v[18:19], off offset:-4096
	s_nop 0
	s_nop 0
	s_nop 0
	s_nop 0
	s_nop 0
	v_mfma_f32_16x16x32_bf16 v[18:21], v[12:15], v[132:135], 0
	v_readlane_b32 s80, v251, 12
	v_readlane_b32 s81, v251, 13
	v_readlane_b32 s82, v251, 14
	s_nop 0
	v_mfma_f32_16x16x32_bf16 v[18:21], v[8:11], v[192:195], v[18:21]
	v_readlane_b32 s83, v251, 15
	s_nop 6
	v_cvt_pk_bf16_f32 v18, v18, v19
	v_cvt_pk_bf16_f32 v19, v20, v21
	global_store_dwordx2 v[26:27], v[18:19], off
	s_nop 0
	s_nop 0
	s_nop 0
	s_nop 0
	s_nop 0
	s_waitcnt lgkmcnt(12)
	v_mfma_f32_16x16x32_bf16 v[18:21], v[12:15], v[196:199], 0
	v_add_co_u32_e32 v26, vcc, s8, v16
	s_movk_i32 s8, 0x7000
	s_nop 0
	s_waitcnt lgkmcnt(10)
	v_mfma_f32_16x16x32_bf16 v[18:21], v[8:11], v[200:203], v[18:21]
	v_addc_co_u32_e32 v27, vcc, 0, v17, vcc
	s_nop 6
	v_cvt_pk_bf16_f32 v18, v18, v19
	v_cvt_pk_bf16_f32 v19, v20, v21
	global_store_dwordx2 v[26:27], v[18:19], off offset:-4096
	s_nop 0
	s_nop 0
	s_nop 0
	s_nop 0
	s_nop 0
	s_waitcnt lgkmcnt(8)
	v_mfma_f32_16x16x32_bf16 v[18:21], v[12:15], v[204:207], 0
	s_nop 0
	s_waitcnt lgkmcnt(6)
	v_mfma_f32_16x16x32_bf16 v[18:21], v[8:11], v[208:211], v[18:21]
	s_nop 7
	v_cvt_pk_bf16_f32 v18, v18, v19
	v_cvt_pk_bf16_f32 v19, v20, v21
	global_store_dwordx2 v[26:27], v[18:19], off
	s_nop 0
	s_nop 0
	s_nop 0
	s_nop 0
	s_nop 0
	s_waitcnt lgkmcnt(4)
	v_mfma_f32_16x16x32_bf16 v[18:21], v[12:15], v[224:227], 0
	s_nop 0
	s_waitcnt lgkmcnt(2)
	v_mfma_f32_16x16x32_bf16 v[18:21], v[8:11], v[228:231], v[18:21]
	s_nop 7
	v_cvt_pk_bf16_f32 v18, v18, v19
	v_cvt_pk_bf16_f32 v19, v20, v21
	v_add_co_u32_e32 v20, vcc, s8, v16
	s_nop 1
	v_addc_co_u32_e32 v21, vcc, 0, v17, vcc
	global_store_dwordx2 v[20:21], v[18:19], off
	s_nop 0
	s_nop 0
	s_nop 0
	s_waitcnt lgkmcnt(0)
	v_mfma_f32_16x16x32_bf16 v[12:15], v[12:15], v[232:235], 0
	ds_read_b64_tr_b16 v[18:19], v190 offset:44800
	ds_read_b64_tr_b16 v[20:21], v190 offset:46016
	s_nop 0
	s_waitcnt lgkmcnt(0)
	v_mfma_f32_16x16x32_bf16 v[8:11], v[8:11], v[18:21], v[12:15]
	s_nop 7
	v_cvt_pk_bf16_f32 v8, v8, v9
	v_cvt_pk_bf16_f32 v9, v10, v11
	v_add_co_u32_e32 v10, vcc, 0x8000, v16
	s_nop 1
	v_addc_co_u32_e32 v11, vcc, 0, v17, vcc
	global_store_dwordx2 v[10:11], v[8:9], off
	s_nop 0
	s_waitcnt lgkmcnt(0)
	s_barrier
